# attention unit prologue: O accumulators zeroed once with 32 v_mov_b64 plus v0..v5 re-zeroed, instead of two passes of 63 v_mov_b32; stacked on stack29
# speedup vs baseline: 1.0099x; 1.0099x over previous
; #define ATT_KAUG(tau_) do { const unsigned tb_ = __float_as_uint((float)((tau_) * KVBLK)) >> 16; \
;         if (hi) { const u32x4 w_ = (u32x4){tb_ | (tb_ << 16), tb_, 0u, 0u}; kaug0 = __builtin_bit_cast(bf16x8, w_); kaug1 = kaug0; } } while (0)
;     ...
;     f32x16 oa0 = f32x16{}, oa1 = f32x16{}, ob0 = f32x16{}, ob1 = f32x16{};
;     f32x16 sa0, sa1, sb0, sb1;
;     u32x4 pa0, pa1, pa2, pa3, pb0, pb1, pb2, pb3;
;     bf16x8 qaA, qaB;
;     const lds_cptr shm3 = (lds_cptr)shm;
;     const lds_cptr kp0 = (lds_cptr)shm + LDS_K + (r32 >> 4) * 1024 + (r32 & 15) * 64 + ((hi) ^ ((r32 >> 2) & 3)) * 16;
;     const int koB = (((2 + hi) ^ ((r32 >> 2) & 3)) - ((hi) ^ ((r32 >> 2) & 3))) * 16;
;     const lds_cptr vp0 = shm3 + LDS_V + ((lane >> 4) & 1) * 32 + (lane & 3) * 8 + (4 * hi + ((lane & 15) >> 2)) * 64;
;     ...
;     ATT_QAUG(ATT_SIDE(d0t)); ATT_KAUG(d0t);
.LBB0_334:
	v_lshlrev_b32_e32 v0, 5, v93
	v_and_b32_e32 v0, 32, v0
	v_or_b32_e32 v1, v172, v97
	v_add_u32_e32 v0, 0, v0
	v_lshlrev_b32_e32 v1, 6, v1
	v_add3_u32 v191, v0, v104, v1
	s_andn2_b64 vcc, exec, s[36:37]
	v_lshl_add_u32 v190, v170, 2, s20
	v_lshl_add_u32 v185, v172, 2, s20
	v_mov_b64_e32 v[0:1], 0
	v_mov_b64_e32 v[2:3], 0
	v_mov_b64_e32 v[4:5], 0
	v_mov_b64_e32 v[6:7], 0
	v_mov_b64_e32 v[8:9], 0
	v_mov_b64_e32 v[10:11], 0
	v_mov_b64_e32 v[12:13], 0
	v_mov_b64_e32 v[14:15], 0
	v_mov_b64_e32 v[16:17], 0
	v_mov_b64_e32 v[18:19], 0
	v_mov_b64_e32 v[20:21], 0
	v_mov_b64_e32 v[22:23], 0
	v_mov_b64_e32 v[24:25], 0
	v_mov_b64_e32 v[26:27], 0
	v_mov_b64_e32 v[28:29], 0
	v_mov_b64_e32 v[30:31], 0
	v_mov_b64_e32 v[32:33], 0
	v_mov_b64_e32 v[34:35], 0
	v_mov_b64_e32 v[36:37], 0
	v_mov_b64_e32 v[38:39], 0
	v_mov_b64_e32 v[40:41], 0
	v_mov_b64_e32 v[42:43], 0
	v_mov_b64_e32 v[44:45], 0
	v_mov_b64_e32 v[46:47], 0
	v_mov_b64_e32 v[48:49], 0
	v_mov_b64_e32 v[50:51], 0
	v_mov_b64_e32 v[52:53], 0
	v_mov_b64_e32 v[54:55], 0
	v_mov_b64_e32 v[56:57], 0
	v_mov_b64_e32 v[58:59], 0
	v_mov_b64_e32 v[60:61], 0
	v_mov_b64_e32 v[62:63], 0
	s_cbranch_vccnz .LBB0_368
	v_cvt_pk_bf16_f32 v4, v98, 0
	v_cndmask_b32_e64 v1, v175, v176, s[40:41]
	v_lshlrev_b32_e32 v4, 16, v4
	v_cndmask_b32_e64 v1, v1, 0, s[62:63]
	v_sub_f32_e32 v4, v98, v4
	v_cvt_pk_bf16_f32 v5, v4, 0
	v_cndmask_b32_e64 v128, 0, v1, s[38:39]
	v_cvt_pk_bf16_f32 v1, v99, 0
	v_cndmask_b32_e64 v2, v177, v178, s[40:41]
	v_lshlrev_b32_e32 v5, 16, v5
	v_lshlrev_b32_e32 v1, 16, v1
	v_cndmask_b32_e64 v2, v2, 0, s[62:63]
	v_sub_f32_e32 v5, v4, v5
	v_cvt_pk_bf16_f32 v4, v98, v4
	v_sub_f32_e32 v1, v99, v1
	v_cndmask_b32_e64 v126, v2, v4, s[38:39]
	v_cvt_pk_bf16_f32 v4, v1, 0
	v_cndmask_b32_e64 v0, v173, -v173, s[40:41]
	v_lshlrev_b32_e32 v4, 16, v4
	v_cndmask_b32_e64 v0, v0, 0, s[62:63]
	v_cndmask_b32_e64 v3, v179, v180, s[40:41]
	v_sub_f32_e32 v4, v1, v4
	v_cndmask_b32_e64 v3, v3, 0, s[62:63]
	v_cvt_pk_bf16_f32 v5, v5, v0
	v_cvt_pk_bf16_f32 v0, v4, v0
	s_or_b32 s21, s21, 64
	v_cndmask_b32_e64 v139, v3, v0, s[38:39]
	v_cvt_f32_u32_e32 v0, s21
	v_cvt_pk_bf16_f32 v1, v99, v1
	v_cndmask_b32_e64 v138, v2, v1, s[38:39]
	s_sub_i32 s20, 64, s14
	v_lshrrev_b32_e32 v1, 16, v0
	v_and_b32_e32 v0, 0x7fff0000, v0
	v_or_b32_e32 v0, v1, v0
	v_cndmask_b32_e64 v127, v3, v5, s[38:39]
	v_cndmask_b32_e64 v130, v0, v96, s[38:39]
	s_sub_i32 s27, s15, s23
	v_xor_b32_e32 v154, 0x80000000, v92
	v_mov_b32_e32 v0, 0
	v_mov_b64_e32 v[144:145], v[128:129]
	s_sub_i32 s19, 64, s23
	v_mov_b32_e32 v140, v128
	v_mov_b32_e32 v141, v129
	v_cndmask_b32_e64 v131, v1, v95, s[38:39]
	v_mov_b32_e32 v133, v129
	v_cndmask_b32_e64 v135, v1, v94, s[38:39]
	v_mov_b32_e32 v134, v130
	v_mov_b32_e32 v137, v129
	s_add_i32 s21, s22, s15
	s_add_i32 s22, s27, 63
	s_sub_i32 s23, 63, s14
	s_max_i32 s26, s20, 2
	v_mov_b32_e32 v156, v154
	v_mov_b32_e32 v157, v154
	s_add_i32 s27, s27, 62
	s_mov_b32 s28, 1
	s_mov_b32 s29, 0x8000
	v_mov_b64_e32 v[142:143], v[126:127]
	v_mov_b64_e32 v[0:1], 0
	v_mov_b64_e32 v[2:3], 0
	v_mov_b64_e32 v[4:5], 0
	v_readfirstlane_b32 s100, v148
	v_readfirstlane_b32 s101, v149
	s_nop 1
	v_subrev_u32_e32 v146, s100, v146
	v_subrev_u32_e32 v148, s100, v148
	v_mov_b32_e32 v112, v191
	v_add_u32_e32 v197, 0x2000, v181
	v_add_u32_e32 v196, v197, v183
	s_branch .LBB0_339
